# SwiGLU GEMM epilogue rewritten by hand: 8 rstd loads hoisted before epilogue barrier, batched shuffles, no per-block vmcnt(0)
# speedup vs baseline: 1.0231x; 1.0231x over previous
; #define PG8_STAGE(bufoff, gbase, voff) do { _Pragma("unroll") for (int _i = 0; _i < 2; ++_i) \
;         __builtin_amdgcn_global_load_lds((const unsigned*)((const char*)(gbase) + (voff)[_i]), (PG8_LAS unsigned*)(lds + (bufoff) + ldsw + _i * 8192), 16, 0, 0); } while (0)
; #define PG8_LDA(dst, b, h) do { _Pragma("unroll") for (int m = 0; m < 4; ++m) _Pragma("unroll") for (int k = 0; k < 2; ++k) dst[m][k] = *(const PG8_LAS bf16x8*)(lds + PG8_SA(b, h) + aoff + m * 2048 + k * 1024); } while (0)
; #define PG8_LDB(dst, b, h) do { _Pragma("unroll") for (int n = 0; n < 2; ++n) _Pragma("unroll") for (int k = 0; k < 2; ++k) dst[n][k] = *(const PG8_LAS bf16x8*)(lds + PG8_SB(b, h) + boff + n * 2048 + k * 1024); } while (0)
; #define PG8_MMA(ai, bj, At, Bt) do { __builtin_amdgcn_s_setprio(1); _Pragma("unroll") for (int m = 0; m < 4; ++m) _Pragma("unroll") for (int n = 0; n < 2; ++n) _Pragma("unroll") for (int k = 0; k < 2; ++k) \
;         acc[ai][bj][m][n] = __builtin_amdgcn_mfma_f32_16x16x32_bf16(Bt[n][k], At[m][k], acc[ai][bj][m][n], 0, 0, 0); __builtin_amdgcn_s_setprio(0); } while (0)
; #define PG8_WAIT_V(n) asm volatile("s_waitcnt vmcnt(" #n ")" ::: "memory")
; #define PG8_WAIT_L(n) asm volatile("s_waitcnt lgkmcnt(" #n ")" ::: "memory")
; #define PG8_BAR __builtin_amdgcn_s_barrier()
; #define PG8_SCHED __builtin_amdgcn_sched_barrier(0)
; template <class Epi, class Sched, bool ALIGN_EPI = false, bool SP2 = false>
; __device__ __forceinline__ void gemm_phase(PG8_LAS unsigned char* lds, const Gemm g, const Sched& S, const Epi& E) {
;     ...
;             PG8_LDB(B0, 0, 0); PG8_LDB(B1, 0, 1); PG8_SCHED; PG8_LDA(At, 0, 0); PG8_STAGE(PG8_SA(1, 1), a1 + hstep, voffA);
;             PG8_WAIT_V(8); PG8_WAIT_L(0); PG8_BAR; PG8_MMA(0, 0, At, B0); PG8_MMA(0, 1, At, B1); PG8_BAR; PG8_SCHED;
;             PG8_LDA(At, 0, 1); PG8_STAGE(PG8_SB(0, 0), b2, voffB); PG8_STAGE(PG8_SB(0, 1), b2 + hstep, voffB); PG8_STAGE(PG8_SA(0, 0), a2, voffA);
;             PG8_WAIT_V(8); PG8_WAIT_L(0); PG8_BAR; PG8_MMA(1, 0, At, B0); PG8_MMA(1, 1, At, B1); PG8_BAR; PG8_SCHED;
.LBB0_493:
	s_add_u32 s24, s22, 0xfffc0080
	s_addc_u32 s25, s23, -1
	s_add_i32 s51, 0, 0x10000
	s_cmp_eq_u32 s50, 12
	s_cselect_b32 s27, s17, s25
	s_cselect_b32 s26, s46, s24
	v_add_u32_e32 v146, s51, v149
	s_cselect_b32 s25, s15, s49
	s_cselect_b32 s24, s47, s48
	s_add_i32 s54, 0, 0x14000
	ds_read_b128 v[142:145], v146
	ds_read_b128 v[152:155], v146 offset:1024
	ds_read_b128 v[172:175], v146 offset:2048
	ds_read_b128 v[176:179], v146 offset:3072
	v_add_u32_e32 v146, s54, v149
	ds_read_b128 v[180:183], v146
	ds_read_b128 v[184:187], v146 offset:1024
	ds_read_b128 v[188:191], v146 offset:2048
	ds_read_b128 v[192:195], v146 offset:3072
	v_lshl_add_u64 v[146:147], s[22:23], 0, v[138:139]
	s_add_i32 m0, s30, 0xc000
	ds_read_b128 v[196:199], v151
	ds_read_b128 v[214:217], v151 offset:1024
	ds_read_b128 v[218:221], v151 offset:2048
	ds_read_b128 v[222:225], v151 offset:3072
	ds_read_b128 v[226:229], v151 offset:4096
	ds_read_b128 v[230:233], v151 offset:5120
	ds_read_b128 v[234:237], v151 offset:6144
	ds_read_b128 v[238:241], v151 offset:7168
	global_load_lds_dwordx4 v[146:147], off
	v_lshl_add_u64 v[146:147], s[22:23], 0, v[140:141]
	s_add_i32 m0, s30, 0xe000
	s_nop 0
	global_load_lds_dwordx4 v[146:147], off
	s_waitcnt vmcnt(8)
	s_waitcnt lgkmcnt(0)
	s_barrier
	s_setprio 1
	s_waitcnt lgkmcnt(0)
	v_mfma_f32_16x16x32_bf16 v[126:129], v[142:145], v[196:199], v[126:129]
	v_mfma_f32_16x16x32_bf16 v[118:121], v[172:175], v[196:199], v[118:121]
	v_mfma_f32_16x16x32_bf16 v[110:113], v[142:145], v[218:221], v[110:113]
	v_mfma_f32_16x16x32_bf16 v[102:105], v[172:175], v[218:221], v[102:105]
	v_mfma_f32_16x16x32_bf16 v[94:97], v[142:145], v[226:229], v[94:97]
	v_mfma_f32_16x16x32_bf16 v[86:89], v[172:175], v[226:229], v[86:89]
	v_mfma_f32_16x16x32_bf16 v[78:81], v[142:145], v[234:237], v[78:81]
	v_mfma_f32_16x16x32_bf16 v[70:73], v[172:175], v[234:237], v[70:73]
	v_mfma_f32_16x16x32_bf16 v[126:129], v[152:155], v[214:217], v[126:129]
	v_mfma_f32_16x16x32_bf16 v[118:121], v[176:179], v[214:217], v[118:121]
	v_mfma_f32_16x16x32_bf16 v[110:113], v[152:155], v[222:225], v[110:113]
	v_mfma_f32_16x16x32_bf16 v[102:105], v[176:179], v[222:225], v[102:105]
	v_mfma_f32_16x16x32_bf16 v[94:97], v[152:155], v[230:233], v[94:97]
	v_mfma_f32_16x16x32_bf16 v[86:89], v[176:179], v[230:233], v[86:89]
	v_mfma_f32_16x16x32_bf16 v[78:81], v[152:155], v[238:241], v[78:81]
	v_mfma_f32_16x16x32_bf16 v[70:73], v[176:179], v[238:241], v[70:73]
	s_setprio 0
	s_setprio 1
	v_mfma_f32_16x16x32_bf16 v[122:125], v[180:183], v[196:199], v[122:125]
	v_mfma_f32_16x16x32_bf16 v[114:117], v[188:191], v[196:199], v[114:117]
	v_mfma_f32_16x16x32_bf16 v[106:109], v[180:183], v[218:221], v[106:109]
	v_mfma_f32_16x16x32_bf16 v[98:101], v[188:191], v[218:221], v[98:101]
	v_mfma_f32_16x16x32_bf16 v[90:93], v[180:183], v[226:229], v[90:93]
	v_mfma_f32_16x16x32_bf16 v[82:85], v[188:191], v[226:229], v[82:85]
	v_mfma_f32_16x16x32_bf16 v[74:77], v[180:183], v[234:237], v[74:77]
	v_mfma_f32_16x16x32_bf16 v[66:69], v[188:191], v[234:237], v[66:69]
	v_mfma_f32_16x16x32_bf16 v[122:125], v[184:187], v[214:217], v[122:125]
	v_mfma_f32_16x16x32_bf16 v[114:117], v[192:195], v[214:217], v[114:117]
	v_mfma_f32_16x16x32_bf16 v[106:109], v[184:187], v[222:225], v[106:109]
	v_mfma_f32_16x16x32_bf16 v[98:101], v[192:195], v[222:225], v[98:101]
	v_mfma_f32_16x16x32_bf16 v[90:93], v[184:187], v[230:233], v[90:93]
	v_mfma_f32_16x16x32_bf16 v[82:85], v[192:195], v[230:233], v[82:85]
	v_mfma_f32_16x16x32_bf16 v[74:77], v[184:187], v[238:241], v[74:77]
	v_mfma_f32_16x16x32_bf16 v[66:69], v[192:195], v[238:241], v[66:69]
	s_setprio 0
	s_barrier
	s_add_i32 s51, s51, s2
	v_lshl_add_u64 v[146:147], s[24:25], 0, v[0:1]
	s_mov_b32 m0, s51
	ds_read_b128 v[196:199], v151 offset:16384
	ds_read_b128 v[214:217], v151 offset:17408
	ds_read_b128 v[218:221], v151 offset:18432
	ds_read_b128 v[222:225], v151 offset:19456
	ds_read_b128 v[226:229], v151 offset:20480
	ds_read_b128 v[230:233], v151 offset:21504
	ds_read_b128 v[234:237], v151 offset:22528
	ds_read_b128 v[238:241], v151 offset:23552
	global_load_lds_dwordx4 v[146:147], off
	s_add_i32 m0, s51, 0x2000
	s_add_u32 s52, s24, 0x40000
	v_lshl_add_u64 v[156:157], s[24:25], 0, v[130:131]
	s_addc_u32 s53, s25, 0
	s_add_i32 s51, s54, s2
	global_load_lds_dwordx4 v[156:157], off
	v_lshl_add_u64 v[242:243], s[52:53], 0, v[0:1]
	s_mov_b32 m0, s51
	v_lshl_add_u64 v[244:245], s[26:27], 0, v[132:133]
	global_load_lds_dwordx4 v[242:243], off
	v_lshl_add_u64 v[242:243], s[52:53], 0, v[130:131]
	s_add_i32 m0, s51, 0x2000
	s_nop 0
	global_load_lds_dwordx4 v[242:243], off
	v_lshl_add_u64 v[242:243], s[26:27], 0, v[134:135]
	s_mov_b32 m0, s30
	s_nop 0
	global_load_lds_dwordx4 v[242:243], off
	s_mov_b32 m0, s31
	s_nop 0
	global_load_lds_dwordx4 v[244:245], off
	s_waitcnt vmcnt(8)
	s_waitcnt lgkmcnt(0)
	s_barrier
; #define PG8_STAGE(bufoff, gbase, voff) do { _Pragma("unroll") for (int _i = 0; _i < 2; ++_i) \
;         __builtin_amdgcn_global_load_lds((const unsigned*)((const char*)(gbase) + (voff)[_i]), (PG8_LAS unsigned*)(lds + (bufoff) + ldsw + _i * 8192), 16, 0, 0); } while (0)
; #define PG8_LDA(dst, b, h) do { _Pragma("unroll") for (int m = 0; m < 4; ++m) _Pragma("unroll") for (int k = 0; k < 2; ++k) dst[m][k] = *(const PG8_LAS bf16x8*)(lds + PG8_SA(b, h) + aoff + m * 2048 + k * 1024); } while (0)
; #define PG8_LDB(dst, b, h) do { _Pragma("unroll") for (int n = 0; n < 2; ++n) _Pragma("unroll") for (int k = 0; k < 2; ++k) dst[n][k] = *(const PG8_LAS bf16x8*)(lds + PG8_SB(b, h) + boff + n * 2048 + k * 1024); } while (0)
; #define PG8_MMA(ai, bj, At, Bt) do { __builtin_amdgcn_s_setprio(1); _Pragma("unroll") for (int m = 0; m < 4; ++m) _Pragma("unroll") for (int n = 0; n < 2; ++n) _Pragma("unroll") for (int k = 0; k < 2; ++k) \
;         acc[ai][bj][m][n] = __builtin_amdgcn_mfma_f32_16x16x32_bf16(Bt[n][k], At[m][k], acc[ai][bj][m][n], 0, 0, 0); __builtin_amdgcn_s_setprio(0); } while (0)
; #define PG8_WAIT_V(n) asm volatile("s_waitcnt vmcnt(" #n ")" ::: "memory")
; #define PG8_WAIT_L(n) asm volatile("s_waitcnt lgkmcnt(" #n ")" ::: "memory")
; #define PG8_BAR __builtin_amdgcn_s_barrier()
; #define PG8_SCHED __builtin_amdgcn_sched_barrier(0)
; template <class Epi, class Sched, bool ALIGN_EPI = false, bool SP2 = false>
; __device__ __forceinline__ void gemm_phase(PG8_LAS unsigned char* lds, const Gemm g, const Sched& S, const Epi& E) {
;     ...
;             PG8_WAIT_V(8); PG8_WAIT_L(0); PG8_BAR; PG8_MMA(1, 0, At, B0); PG8_MMA(1, 1, At, B1); PG8_BAR; PG8_SCHED;
;             PG8_LDB(B0, 1, 0); PG8_LDB(B1, 1, 1); PG8_SCHED; PG8_LDA(At, 1, 0); PG8_STAGE(PG8_SA(0, 1), a2 + hstep, voffA);
;             PG8_WAIT_V(8); PG8_WAIT_L(0); PG8_BAR; PG8_MMA(0, 0, At, B0); PG8_MMA(0, 1, At, B1); PG8_BAR; PG8_SCHED;
;             PG8_LDA(At, 1, 1); PG8_STAGE(PG8_SB(1, 0), b3, voffB); PG8_STAGE(PG8_SB(1, 1), b3 + hstep, voffB); PG8_STAGE(PG8_SA(1, 0), a3, voffA);
;             PG8_WAIT_V(8); PG8_WAIT_L(0); PG8_BAR; PG8_MMA(1, 0, At, B0); PG8_MMA(1, 1, At, B1); PG8_BAR; PG8_SCHED;
	s_setprio 1
	s_waitcnt lgkmcnt(0)
	v_mfma_f32_16x16x32_bf16 v[62:65], v[142:145], v[196:199], v[62:65]
	v_mfma_f32_16x16x32_bf16 v[54:57], v[172:175], v[196:199], v[54:57]
	v_mfma_f32_16x16x32_bf16 v[46:49], v[142:145], v[218:221], v[46:49]
	v_mfma_f32_16x16x32_bf16 v[38:41], v[172:175], v[218:221], v[38:41]
	v_mfma_f32_16x16x32_bf16 v[30:33], v[142:145], v[226:229], v[30:33]
	v_mfma_f32_16x16x32_bf16 v[22:25], v[172:175], v[226:229], v[22:25]
	v_mfma_f32_16x16x32_bf16 v[14:17], v[142:145], v[234:237], v[14:17]
	v_mfma_f32_16x16x32_bf16 v[6:9], v[172:175], v[234:237], v[6:9]
	v_mfma_f32_16x16x32_bf16 v[62:65], v[152:155], v[214:217], v[62:65]
	v_mfma_f32_16x16x32_bf16 v[54:57], v[176:179], v[214:217], v[54:57]
	v_mfma_f32_16x16x32_bf16 v[46:49], v[152:155], v[222:225], v[46:49]
	v_mfma_f32_16x16x32_bf16 v[38:41], v[176:179], v[222:225], v[38:41]
	v_mfma_f32_16x16x32_bf16 v[30:33], v[152:155], v[230:233], v[30:33]
	v_mfma_f32_16x16x32_bf16 v[22:25], v[176:179], v[230:233], v[22:25]
	v_mfma_f32_16x16x32_bf16 v[14:17], v[152:155], v[238:241], v[14:17]
	v_mfma_f32_16x16x32_bf16 v[6:9], v[176:179], v[238:241], v[6:9]
	s_setprio 0
	s_setprio 1
	v_mfma_f32_16x16x32_bf16 v[58:61], v[180:183], v[196:199], v[58:61]
	v_mfma_f32_16x16x32_bf16 v[50:53], v[188:191], v[196:199], v[50:53]
	v_mfma_f32_16x16x32_bf16 v[42:45], v[180:183], v[218:221], v[42:45]
	v_mfma_f32_16x16x32_bf16 v[34:37], v[188:191], v[218:221], v[34:37]
	v_mfma_f32_16x16x32_bf16 v[26:29], v[180:183], v[226:229], v[26:29]
	v_mfma_f32_16x16x32_bf16 v[18:21], v[188:191], v[226:229], v[18:21]
	v_mfma_f32_16x16x32_bf16 v[10:13], v[180:183], v[234:237], v[10:13]
	v_mfma_f32_16x16x32_bf16 v[2:5], v[188:191], v[234:237], v[2:5]
	v_mfma_f32_16x16x32_bf16 v[58:61], v[184:187], v[214:217], v[58:61]
	v_mfma_f32_16x16x32_bf16 v[50:53], v[192:195], v[214:217], v[50:53]
	v_mfma_f32_16x16x32_bf16 v[42:45], v[184:187], v[222:225], v[42:45]
	v_mfma_f32_16x16x32_bf16 v[34:37], v[192:195], v[222:225], v[34:37]
	v_mfma_f32_16x16x32_bf16 v[26:29], v[184:187], v[230:233], v[26:29]
	v_mfma_f32_16x16x32_bf16 v[18:21], v[192:195], v[230:233], v[18:21]
	v_mfma_f32_16x16x32_bf16 v[10:13], v[184:187], v[238:241], v[10:13]
	v_mfma_f32_16x16x32_bf16 v[2:5], v[192:195], v[238:241], v[2:5]
	s_setprio 0
	s_barrier
	s_add_i32 s51, 0, 0x18000
	v_add_u32_e32 v158, s51, v149
	s_add_i32 s52, 0, 0x1c000
	ds_read_b128 v[142:145], v158
	ds_read_b128 v[152:155], v158 offset:1024
	ds_read_b128 v[172:175], v158 offset:2048
	ds_read_b128 v[176:179], v158 offset:3072
	v_add_u32_e32 v158, s52, v149
	ds_read_b128 v[180:183], v158
	ds_read_b128 v[184:187], v158 offset:1024
	ds_read_b128 v[188:191], v158 offset:2048
	ds_read_b128 v[192:195], v158 offset:3072
	s_add_u32 s26, s26, 0x40000
	s_addc_u32 s27, s27, 0
	s_mov_b32 m0, s34
	v_lshl_add_u64 v[246:247], s[26:27], 0, v[134:135]
	ds_read_b128 v[196:199], v151 offset:32768
	ds_read_b128 v[214:217], v151 offset:33792
	ds_read_b128 v[218:221], v151 offset:34816
	ds_read_b128 v[222:225], v151 offset:35840
	ds_read_b128 v[226:229], v151 offset:36864
	ds_read_b128 v[230:233], v151 offset:37888
	ds_read_b128 v[234:237], v151 offset:38912
	ds_read_b128 v[238:241], v151 offset:39936
	global_load_lds_dwordx4 v[246:247], off
	v_lshl_add_u64 v[246:247], s[26:27], 0, v[132:133]
	s_mov_b32 m0, s35
	s_nop 0
	global_load_lds_dwordx4 v[246:247], off
	s_waitcnt vmcnt(8)
	s_waitcnt lgkmcnt(0)
	s_barrier
	s_setprio 1
	s_waitcnt lgkmcnt(0)
	v_mfma_f32_16x16x32_bf16 v[126:129], v[142:145], v[196:199], v[126:129]
	v_mfma_f32_16x16x32_bf16 v[118:121], v[172:175], v[196:199], v[118:121]
	v_mfma_f32_16x16x32_bf16 v[110:113], v[142:145], v[218:221], v[110:113]
	v_mfma_f32_16x16x32_bf16 v[102:105], v[172:175], v[218:221], v[102:105]
	v_mfma_f32_16x16x32_bf16 v[94:97], v[142:145], v[226:229], v[94:97]
	v_mfma_f32_16x16x32_bf16 v[86:89], v[172:175], v[226:229], v[86:89]
	v_mfma_f32_16x16x32_bf16 v[78:81], v[142:145], v[234:237], v[78:81]
	v_mfma_f32_16x16x32_bf16 v[70:73], v[172:175], v[234:237], v[70:73]
	v_mfma_f32_16x16x32_bf16 v[126:129], v[152:155], v[214:217], v[126:129]
	v_mfma_f32_16x16x32_bf16 v[118:121], v[176:179], v[214:217], v[118:121]
	v_mfma_f32_16x16x32_bf16 v[110:113], v[152:155], v[222:225], v[110:113]
	v_mfma_f32_16x16x32_bf16 v[102:105], v[176:179], v[222:225], v[102:105]
	v_mfma_f32_16x16x32_bf16 v[94:97], v[152:155], v[230:233], v[94:97]
	v_mfma_f32_16x16x32_bf16 v[86:89], v[176:179], v[230:233], v[86:89]
	v_mfma_f32_16x16x32_bf16 v[78:81], v[152:155], v[238:241], v[78:81]
	v_mfma_f32_16x16x32_bf16 v[70:73], v[176:179], v[238:241], v[70:73]
	s_setprio 0
	s_setprio 1
	v_mfma_f32_16x16x32_bf16 v[122:125], v[180:183], v[196:199], v[122:125]
	v_mfma_f32_16x16x32_bf16 v[114:117], v[188:191], v[196:199], v[114:117]
	v_mfma_f32_16x16x32_bf16 v[106:109], v[180:183], v[218:221], v[106:109]
	v_mfma_f32_16x16x32_bf16 v[98:101], v[188:191], v[218:221], v[98:101]
	v_mfma_f32_16x16x32_bf16 v[90:93], v[180:183], v[226:229], v[90:93]
	v_mfma_f32_16x16x32_bf16 v[82:85], v[188:191], v[226:229], v[82:85]
	v_mfma_f32_16x16x32_bf16 v[74:77], v[180:183], v[234:237], v[74:77]
	v_mfma_f32_16x16x32_bf16 v[66:69], v[188:191], v[234:237], v[66:69]
	v_mfma_f32_16x16x32_bf16 v[122:125], v[184:187], v[214:217], v[122:125]
	v_mfma_f32_16x16x32_bf16 v[114:117], v[192:195], v[214:217], v[114:117]
	v_mfma_f32_16x16x32_bf16 v[106:109], v[184:187], v[222:225], v[106:109]
	v_mfma_f32_16x16x32_bf16 v[98:101], v[192:195], v[222:225], v[98:101]
	v_mfma_f32_16x16x32_bf16 v[90:93], v[184:187], v[230:233], v[90:93]
	v_mfma_f32_16x16x32_bf16 v[82:85], v[192:195], v[230:233], v[82:85]
	v_mfma_f32_16x16x32_bf16 v[74:77], v[184:187], v[238:241], v[74:77]
	v_mfma_f32_16x16x32_bf16 v[66:69], v[192:195], v[238:241], v[66:69]
	s_setprio 0
	s_barrier
; #define PG8_STAGE(bufoff, gbase, voff) do { _Pragma("unroll") for (int _i = 0; _i < 2; ++_i) \
;         __builtin_amdgcn_global_load_lds((const unsigned*)((const char*)(gbase) + (voff)[_i]), (PG8_LAS unsigned*)(lds + (bufoff) + ldsw + _i * 8192), 16, 0, 0); } while (0)
; #define PG8_LDA(dst, b, h) do { _Pragma("unroll") for (int m = 0; m < 4; ++m) _Pragma("unroll") for (int k = 0; k < 2; ++k) dst[m][k] = *(const PG8_LAS bf16x8*)(lds + PG8_SA(b, h) + aoff + m * 2048 + k * 1024); } while (0)
; #define PG8_MMA(ai, bj, At, Bt) do { __builtin_amdgcn_s_setprio(1); _Pragma("unroll") for (int m = 0; m < 4; ++m) _Pragma("unroll") for (int n = 0; n < 2; ++n) _Pragma("unroll") for (int k = 0; k < 2; ++k) \
;         acc[ai][bj][m][n] = __builtin_amdgcn_mfma_f32_16x16x32_bf16(Bt[n][k], At[m][k], acc[ai][bj][m][n], 0, 0, 0); __builtin_amdgcn_s_setprio(0); } while (0)
; #define PG8_WAIT_V(n) asm volatile("s_waitcnt vmcnt(" #n ")" ::: "memory")
; #define PG8_WAIT_L(n) asm volatile("s_waitcnt lgkmcnt(" #n ")" ::: "memory")
; #define PG8_BAR __builtin_amdgcn_s_barrier()
; #define PG8_SCHED __builtin_amdgcn_sched_barrier(0)
; template <class Epi, class Sched, bool ALIGN_EPI = false, bool SP2 = false>
; __device__ __forceinline__ void gemm_phase(PG8_LAS unsigned char* lds, const Gemm g, const Sched& S, const Epi& E) {
;     ...
;             PG8_LDA(At, 1, 1); PG8_STAGE(PG8_SB(1, 0), b3, voffB); PG8_STAGE(PG8_SB(1, 1), b3 + hstep, voffB); PG8_STAGE(PG8_SA(1, 0), a3, voffA);
;             PG8_WAIT_V(8); PG8_WAIT_L(0); PG8_BAR; PG8_MMA(1, 0, At, B0); PG8_MMA(1, 1, At, B1); PG8_BAR; PG8_SCHED;
; __device__ __forceinline__ float row_rstd(const float* rsp, int row, int fq) {
;     const f32x4 v = *(const f32x4*)(rsp + (size_t)row * 16 + 4 * fq);
;     float s = (v[0] + v[1]) + (v[2] + v[3]); s += __shfl_xor(s, 16); s += __shfl_xor(s, 32);
;     return rsqrtf(s * (1.0f / 1024.0f) + RMS_EPS);
; }
;     __device__ __forceinline__ void operator()(const f32x4 (&acc)[2][2][4][2], const Unit& u, int wr, int wc, int fr, int fq) const {
;         const int row0 = u.pm * BM + wr * 64 + fr, col0 = u.pn * HALF + wc * 32 + 8 * fq;
; #pragma unroll
;         for (int ai = 0; ai < 2; ++ai)
; #pragma unroll
;             for (int m = 0; m < 4; ++m) {
;                 const int row = row0 + ai * HALF + m * 16; const float rs = row_rstd(rsp, row, fq);
	s_add_i32 s26, s51, s2
	v_lshl_add_u64 v[146:147], v[146:147], 0, s[90:91]
	s_mov_b32 m0, s26
	ds_read_b128 v[196:199], v151 offset:49152
	ds_read_b128 v[214:217], v151 offset:50176
	ds_read_b128 v[218:221], v151 offset:51200
	ds_read_b128 v[222:225], v151 offset:52224
	ds_read_b128 v[226:229], v151 offset:53248
	ds_read_b128 v[230:233], v151 offset:54272
	ds_read_b128 v[234:237], v151 offset:55296
	ds_read_b128 v[238:241], v151 offset:56320
	global_load_lds_dwordx4 v[146:147], off
	s_add_i32 m0, s26, 0x2000
	s_add_u32 s24, s24, 0x40080
	v_lshl_add_u64 v[146:147], v[156:157], 0, s[90:91]
	s_addc_u32 s25, s25, 0
	s_add_i32 s26, s52, s2
	global_load_lds_dwordx4 v[146:147], off
	v_lshl_add_u64 v[146:147], s[24:25], 0, v[0:1]
	s_mov_b32 m0, s26
	s_nop 0
	global_load_lds_dwordx4 v[146:147], off
	v_lshl_add_u64 v[146:147], s[24:25], 0, v[130:131]
	s_add_i32 m0, s26, 0x2000
	s_nop 0
	global_load_lds_dwordx4 v[146:147], off
	v_lshl_add_u64 v[146:147], v[242:243], 0, s[90:91]
	s_mov_b32 m0, s37
	s_nop 0
	global_load_lds_dwordx4 v[146:147], off
	v_lshl_add_u64 v[146:147], v[244:245], 0, s[90:91]
	s_mov_b32 m0, s38
	s_nop 0
	global_load_lds_dwordx4 v[146:147], off
	s_waitcnt vmcnt(8)
	s_waitcnt lgkmcnt(0)
	s_barrier
	s_setprio 1
	s_waitcnt lgkmcnt(0)
	v_mfma_f32_16x16x32_bf16 v[62:65], v[142:145], v[196:199], v[62:65]
	v_mfma_f32_16x16x32_bf16 v[54:57], v[172:175], v[196:199], v[54:57]
	v_mfma_f32_16x16x32_bf16 v[46:49], v[142:145], v[218:221], v[46:49]
	v_mfma_f32_16x16x32_bf16 v[38:41], v[172:175], v[218:221], v[38:41]
	v_mfma_f32_16x16x32_bf16 v[30:33], v[142:145], v[226:229], v[30:33]
	v_mfma_f32_16x16x32_bf16 v[22:25], v[172:175], v[226:229], v[22:25]
	v_mfma_f32_16x16x32_bf16 v[14:17], v[142:145], v[234:237], v[14:17]
	v_mfma_f32_16x16x32_bf16 v[6:9], v[172:175], v[234:237], v[6:9]
	v_mfma_f32_16x16x32_bf16 v[62:65], v[152:155], v[214:217], v[62:65]
	v_mfma_f32_16x16x32_bf16 v[54:57], v[176:179], v[214:217], v[54:57]
	v_mfma_f32_16x16x32_bf16 v[46:49], v[152:155], v[222:225], v[46:49]
	v_mfma_f32_16x16x32_bf16 v[38:41], v[176:179], v[222:225], v[38:41]
	v_mfma_f32_16x16x32_bf16 v[30:33], v[152:155], v[230:233], v[30:33]
	v_mfma_f32_16x16x32_bf16 v[22:25], v[176:179], v[230:233], v[22:25]
	v_mfma_f32_16x16x32_bf16 v[14:17], v[152:155], v[238:241], v[14:17]
	v_mfma_f32_16x16x32_bf16 v[6:9], v[176:179], v[238:241], v[6:9]
	s_setprio 0
	s_setprio 1
	v_mfma_f32_16x16x32_bf16 v[58:61], v[180:183], v[196:199], v[58:61]
	v_mfma_f32_16x16x32_bf16 v[50:53], v[188:191], v[196:199], v[50:53]
	v_mfma_f32_16x16x32_bf16 v[42:45], v[180:183], v[218:221], v[42:45]
	v_mfma_f32_16x16x32_bf16 v[34:37], v[188:191], v[218:221], v[34:37]
	v_mfma_f32_16x16x32_bf16 v[26:29], v[180:183], v[226:229], v[26:29]
	v_mfma_f32_16x16x32_bf16 v[18:21], v[188:191], v[226:229], v[18:21]
	v_mfma_f32_16x16x32_bf16 v[10:13], v[180:183], v[234:237], v[10:13]
	v_mfma_f32_16x16x32_bf16 v[2:5], v[188:191], v[234:237], v[2:5]
	v_mfma_f32_16x16x32_bf16 v[58:61], v[184:187], v[214:217], v[58:61]
	v_mfma_f32_16x16x32_bf16 v[50:53], v[192:195], v[214:217], v[50:53]
	v_mfma_f32_16x16x32_bf16 v[42:45], v[184:187], v[222:225], v[42:45]
	v_mfma_f32_16x16x32_bf16 v[34:37], v[192:195], v[222:225], v[34:37]
	v_mfma_f32_16x16x32_bf16 v[26:29], v[184:187], v[230:233], v[26:29]
	v_mfma_f32_16x16x32_bf16 v[18:21], v[192:195], v[230:233], v[18:21]
	v_mfma_f32_16x16x32_bf16 v[10:13], v[184:187], v[238:241], v[10:13]
	v_mfma_f32_16x16x32_bf16 v[2:5], v[192:195], v[238:241], v[2:5]
	s_setprio 0
	s_barrier
	s_add_i32 s50, s50, 2
	s_add_u32 s22, s22, 0x100
	s_addc_u32 s23, s23, 0
	s_add_u32 s48, s48, 0x100
	s_addc_u32 s49, s49, 0
	s_cmp_gt_u32 s50, 13
	s_cbranch_scc0 .LBB0_493
	v_lshl_add_u32 v142, s45, 8, v148
	v_mov_b32_e32 v143, 0
	s_mov_b32 s26, 0x2000
	s_mov_b32 s27, 0
	v_lshlrev_b64 v[146:147], 6, v[142:143]
	v_lshl_add_u64 v[146:147], v[136:137], 0, v[146:147]
	v_lshl_add_u64 v[156:157], v[146:147], 0, s[26:27]
	global_load_dwordx4 v[172:175], v[146:147], off
	global_load_dwordx4 v[176:179], v[146:147], off offset:1024
	global_load_dwordx4 v[180:183], v[146:147], off offset:2048
	global_load_dwordx4 v[184:187], v[146:147], off offset:3072
	global_load_dwordx4 v[188:191], v[156:157], off
	global_load_dwordx4 v[192:195], v[156:157], off offset:1024
	global_load_dwordx4 v[196:199], v[156:157], off offset:2048
	global_load_dwordx4 v[214:217], v[156:157], off offset:3072
	v_xor_b32_e32 v152, 16, v201
	v_xor_b32_e32 v153, 32, v201
	v_lshlrev_b32_e32 v152, 2, v152
	v_lshlrev_b32_e32 v153, 2, v153
	v_lshl_or_b32 v144, s44, 7, v150
	v_mov_b32_e32 v145, 0
	v_mov_b32_e32 v238, s0
	v_mov_b32_e32 v239, s1
	v_mad_i64_i32 v[236:237], s[22:23], v142, s93, v[238:239]
	v_lshlrev_b64 v[240:241], 1, v[144:145]
	v_mov_b32_e32 v234, 1.0
	v_mov_b32_e32 v235, 1.0
	v_lshl_add_u64 v[236:237], v[236:237], 0, v[240:241]
	s_mov_b32 s26, 0x16000
	s_mov_b32 s24, 0x6e000
	s_mov_b32 s25, 0
	s_and_b64 vcc, exec, s[12:13]
	s_cbranch_vccz .LBB0_496
	s_barrier
; __device__ __forceinline__ float row_rstd(const float* rsp, int row, int fq) {
;     const f32x4 v = *(const f32x4*)(rsp + (size_t)row * 16 + 4 * fq);
;     float s = (v[0] + v[1]) + (v[2] + v[3]); s += __shfl_xor(s, 16); s += __shfl_xor(s, 32);
;     return rsqrtf(s * (1.0f / 1024.0f) + RMS_EPS);
;     __device__ __forceinline__ void operator()(const f32x4 (&acc)[2][2][4][2], const Unit& u, int wr, int wc, int fr, int fq) const {
;     ...
;                 const int row = row0 + ai * HALF + m * 16; const float rs = row_rstd(rsp, row, fq);
;                 const float nrs = -LOG2E * rs, rs2 = rs * rs;
;                 const f32x4 g0 = acc[ai][0][m][0], g1 = acc[ai][0][m][1], u0 = acc[ai][1][m][0], u1 = acc[ai][1][m][1];
;                 const f32x4 a0 = g0 * nrs, a1 = g1 * nrs;
;                 f32x4 e0, e1;
; #pragma unroll
;                 for (int q = 0; q < 4; ++q) { e0[q] = __builtin_amdgcn_exp2f(a0[q]); e1[q] = __builtin_amdgcn_exp2f(a1[q]); }
;                 const f32x4 d0 = e0 + 1.0f, d1 = e1 + 1.0f;
;                 f32x4 r0, r1;
; #pragma unroll
;                 for (int q = 0; q < 4; ++q) { r0[q] = __builtin_amdgcn_rcpf(d0[q]); r1[q] = __builtin_amdgcn_rcpf(d1[q]); }
;                 const f32x4 o0 = ((g0 * u0) * rs2) * r0, o1 = ((g1 * u1) * rs2) * r1;
.LBB0_496:
	v_pk_mul_f32 v[122:123], v[126:127], v[122:123]
	v_pk_mul_f32 v[124:125], v[128:129], v[124:125]
	v_pk_mul_f32 v[114:115], v[118:119], v[114:115]
	v_pk_mul_f32 v[116:117], v[120:121], v[116:117]
	v_pk_mul_f32 v[106:107], v[110:111], v[106:107]
	v_pk_mul_f32 v[108:109], v[112:113], v[108:109]
	v_pk_mul_f32 v[98:99], v[102:103], v[98:99]
	v_pk_mul_f32 v[100:101], v[104:105], v[100:101]
	v_pk_mul_f32 v[90:91], v[94:95], v[90:91]
	v_pk_mul_f32 v[92:93], v[96:97], v[92:93]
	v_pk_mul_f32 v[82:83], v[86:87], v[82:83]
	v_pk_mul_f32 v[84:85], v[88:89], v[84:85]
	v_pk_mul_f32 v[74:75], v[78:79], v[74:75]
	v_pk_mul_f32 v[76:77], v[80:81], v[76:77]
	v_pk_mul_f32 v[66:67], v[70:71], v[66:67]
	v_pk_mul_f32 v[68:69], v[72:73], v[68:69]
	v_pk_mul_f32 v[58:59], v[62:63], v[58:59]
	v_pk_mul_f32 v[60:61], v[64:65], v[60:61]
	v_pk_mul_f32 v[50:51], v[54:55], v[50:51]
	v_pk_mul_f32 v[52:53], v[56:57], v[52:53]
	v_pk_mul_f32 v[42:43], v[46:47], v[42:43]
	v_pk_mul_f32 v[44:45], v[48:49], v[44:45]
	v_pk_mul_f32 v[34:35], v[38:39], v[34:35]
	v_pk_mul_f32 v[36:37], v[40:41], v[36:37]
	v_pk_mul_f32 v[26:27], v[30:31], v[26:27]
	v_pk_mul_f32 v[28:29], v[32:33], v[28:29]
	v_pk_mul_f32 v[18:19], v[22:23], v[18:19]
	v_pk_mul_f32 v[20:21], v[24:25], v[20:21]
	v_pk_mul_f32 v[10:11], v[14:15], v[10:11]
	v_pk_mul_f32 v[12:13], v[16:17], v[12:13]
	v_pk_mul_f32 v[2:3], v[6:7], v[2:3]
	v_pk_mul_f32 v[4:5], v[8:9], v[4:5]
	s_waitcnt vmcnt(0)
	v_add_f32_e32 v172, v172, v173
	v_add_f32_e32 v176, v176, v177
	v_add_f32_e32 v180, v180, v181
	v_add_f32_e32 v184, v184, v185
	v_add_f32_e32 v188, v188, v189
	v_add_f32_e32 v192, v192, v193
	v_add_f32_e32 v196, v196, v197
	v_add_f32_e32 v214, v214, v215
	v_add_f32_e32 v174, v174, v175
	v_add_f32_e32 v178, v178, v179
	v_add_f32_e32 v182, v182, v183
	v_add_f32_e32 v186, v186, v187
	v_add_f32_e32 v190, v190, v191
	v_add_f32_e32 v194, v194, v195
	v_add_f32_e32 v198, v198, v199
	v_add_f32_e32 v216, v216, v217
	v_add_f32_e32 v172, v172, v174
	v_add_f32_e32 v176, v176, v178
	v_add_f32_e32 v180, v180, v182
	v_add_f32_e32 v184, v184, v186
	v_add_f32_e32 v188, v188, v190
	v_add_f32_e32 v192, v192, v194
	v_add_f32_e32 v196, v196, v198
	v_add_f32_e32 v214, v214, v216
	ds_bpermute_b32 v173, v152, v172
	ds_bpermute_b32 v177, v152, v176
	ds_bpermute_b32 v181, v152, v180
	ds_bpermute_b32 v185, v152, v184
	ds_bpermute_b32 v189, v152, v188
	ds_bpermute_b32 v193, v152, v192
	ds_bpermute_b32 v197, v152, v196
	ds_bpermute_b32 v215, v152, v214
	s_waitcnt lgkmcnt(0)
	v_add_f32_e32 v172, v172, v173
	v_add_f32_e32 v176, v176, v177
	v_add_f32_e32 v180, v180, v181
	v_add_f32_e32 v184, v184, v185
	v_add_f32_e32 v188, v188, v189
	v_add_f32_e32 v192, v192, v193
	v_add_f32_e32 v196, v196, v197
	v_add_f32_e32 v214, v214, v215
	ds_bpermute_b32 v173, v153, v172
	ds_bpermute_b32 v177, v153, v176
	ds_bpermute_b32 v181, v153, v180
	ds_bpermute_b32 v185, v153, v184
	ds_bpermute_b32 v189, v153, v188
	ds_bpermute_b32 v193, v153, v192
	ds_bpermute_b32 v197, v153, v196
	ds_bpermute_b32 v215, v153, v214
	s_waitcnt lgkmcnt(0)
	v_add_f32_e32 v172, v172, v173
	v_add_f32_e32 v176, v176, v177
	v_add_f32_e32 v180, v180, v181
	v_add_f32_e32 v184, v184, v185
	v_add_f32_e32 v188, v188, v189
	v_add_f32_e32 v192, v192, v193
	v_add_f32_e32 v196, v196, v197
	v_add_f32_e32 v214, v214, v215
	v_fmamk_f32 v172, v172, 0x3a800000, v207
	v_fmamk_f32 v176, v176, 0x3a800000, v207
	v_fmamk_f32 v180, v180, 0x3a800000, v207
	v_fmamk_f32 v184, v184, 0x3a800000, v207
	v_fmamk_f32 v188, v188, 0x3a800000, v207
	v_fmamk_f32 v192, v192, 0x3a800000, v207
	v_fmamk_f32 v196, v196, 0x3a800000, v207
	v_fmamk_f32 v214, v214, 0x3a800000, v207
	v_rsq_f32_e32 v172, v172
	v_rsq_f32_e32 v176, v176
	v_rsq_f32_e32 v180, v180
	v_rsq_f32_e32 v184, v184
	v_rsq_f32_e32 v188, v188
	v_rsq_f32_e32 v192, v192
	v_rsq_f32_e32 v196, v196
	v_rsq_f32_e32 v214, v214
	v_mul_f32_e32 v174, v172, v172
	v_mul_f32_e32 v178, v176, v176
	v_mul_f32_e32 v182, v180, v180
	v_mul_f32_e32 v186, v184, v184
	v_mul_f32_e32 v190, v188, v188
	v_mul_f32_e32 v194, v192, v192
	v_mul_f32_e32 v198, v196, v196
	v_mul_f32_e32 v216, v214, v214
	v_mul_f32_e32 v172, 0xbfb8aa3b, v172
	v_mul_f32_e32 v176, 0xbfb8aa3b, v176
	v_mul_f32_e32 v180, 0xbfb8aa3b, v180
	v_mul_f32_e32 v184, 0xbfb8aa3b, v184
	v_mul_f32_e32 v188, 0xbfb8aa3b, v188
	v_mul_f32_e32 v192, 0xbfb8aa3b, v192
	v_mul_f32_e32 v196, 0xbfb8aa3b, v196
	v_mul_f32_e32 v214, 0xbfb8aa3b, v214
	v_pk_mul_f32 v[218:219], v[126:127], v[172:173] op_sel_hi:[1,0]
	v_pk_mul_f32 v[220:221], v[128:129], v[172:173] op_sel_hi:[1,0]
	v_pk_mul_f32 v[222:223], v[118:119], v[172:173] op_sel_hi:[1,0]
	v_pk_mul_f32 v[224:225], v[120:121], v[172:173] op_sel_hi:[1,0]
	v_exp_f32_e32 v218, v218
	v_exp_f32_e32 v219, v219
	v_exp_f32_e32 v220, v220
	v_exp_f32_e32 v221, v221
	v_exp_f32_e32 v222, v222
	v_exp_f32_e32 v223, v223
	v_exp_f32_e32 v224, v224
	v_exp_f32_e32 v225, v225
	v_pk_add_f32 v[218:219], v[218:219], v[234:235]
	v_pk_add_f32 v[220:221], v[220:221], v[234:235]
	v_pk_add_f32 v[222:223], v[222:223], v[234:235]
	v_pk_add_f32 v[224:225], v[224:225], v[234:235]
	v_rcp_f32_e32 v218, v218
	v_rcp_f32_e32 v219, v219
	v_rcp_f32_e32 v220, v220
	v_rcp_f32_e32 v221, v221
	v_rcp_f32_e32 v222, v222
	v_rcp_f32_e32 v223, v223
	v_rcp_f32_e32 v224, v224
	v_rcp_f32_e32 v225, v225
	v_pk_mul_f32 v[122:123], v[122:123], v[174:175] op_sel_hi:[1,0]
	v_pk_mul_f32 v[124:125], v[124:125], v[174:175] op_sel_hi:[1,0]
	v_pk_mul_f32 v[114:115], v[114:115], v[174:175] op_sel_hi:[1,0]
	v_pk_mul_f32 v[116:117], v[116:117], v[174:175] op_sel_hi:[1,0]
	v_pk_mul_f32 v[122:123], v[122:123], v[218:219]
	v_pk_mul_f32 v[124:125], v[124:125], v[220:221]
; __device__ __forceinline__ unsigned cvt_pk_bf16(float lo, float hi) { f32x2_cv v = {lo, hi}; bf16x2_cv b = __builtin_convertvector(v, bf16x2_cv); return __builtin_bit_cast(unsigned, b); }
;     __device__ __forceinline__ void operator()(const f32x4 (&acc)[2][2][4][2], const Unit& u, int wr, int wc, int fr, int fq) const {
;     ...
;             for (int m = 0; m < 4; ++m) {
;                 const int row = row0 + ai * HALF + m * 16; const float rs = row_rstd(rsp, row, fq);
;                 const float nrs = -LOG2E * rs, rs2 = rs * rs;
;                 const f32x4 g0 = acc[ai][0][m][0], g1 = acc[ai][0][m][1], u0 = acc[ai][1][m][0], u1 = acc[ai][1][m][1];
;                 const f32x4 a0 = g0 * nrs, a1 = g1 * nrs;
;                 f32x4 e0, e1;
; #pragma unroll
;                 for (int q = 0; q < 4; ++q) { e0[q] = __builtin_amdgcn_exp2f(a0[q]); e1[q] = __builtin_amdgcn_exp2f(a1[q]); }
;                 const f32x4 d0 = e0 + 1.0f, d1 = e1 + 1.0f;
;                 f32x4 r0, r1;
; #pragma unroll
;                 for (int q = 0; q < 4; ++q) { r0[q] = __builtin_amdgcn_rcpf(d0[q]); r1[q] = __builtin_amdgcn_rcpf(d1[q]); }
;                 const f32x4 o0 = ((g0 * u0) * rs2) * r0, o1 = ((g1 * u1) * rs2) * r1;
;                 u32x4 w; w.x = cvt_pk_bf16(o0[0], o0[1]); w.y = cvt_pk_bf16(o0[2], o0[3]); w.z = cvt_pk_bf16(o1[0], o1[1]); w.w = cvt_pk_bf16(o1[2], o1[3]);
;                 *(u32x4*)(O + (size_t)row * ldc + col0) = w;
	v_pk_mul_f32 v[114:115], v[114:115], v[222:223]
	v_pk_mul_f32 v[116:117], v[116:117], v[224:225]
	v_cvt_pk_bf16_f32 v118, v122, v123
	v_cvt_pk_bf16_f32 v119, v124, v125
	v_cvt_pk_bf16_f32 v120, v114, v115
	v_cvt_pk_bf16_f32 v121, v116, v117
	global_store_dwordx4 v[236:237], v[118:121], off
	v_lshl_add_u64 v[236:237], v[236:237], 0, s[26:27]
	v_pk_mul_f32 v[226:227], v[110:111], v[176:177] op_sel_hi:[1,0]
	v_pk_mul_f32 v[228:229], v[112:113], v[176:177] op_sel_hi:[1,0]
	v_pk_mul_f32 v[230:231], v[102:103], v[176:177] op_sel_hi:[1,0]
	v_pk_mul_f32 v[232:233], v[104:105], v[176:177] op_sel_hi:[1,0]
	v_exp_f32_e32 v226, v226
	v_exp_f32_e32 v227, v227
	v_exp_f32_e32 v228, v228
	v_exp_f32_e32 v229, v229
	v_exp_f32_e32 v230, v230
	v_exp_f32_e32 v231, v231
	v_exp_f32_e32 v232, v232
	v_exp_f32_e32 v233, v233
	v_pk_add_f32 v[226:227], v[226:227], v[234:235]
	v_pk_add_f32 v[228:229], v[228:229], v[234:235]
	v_pk_add_f32 v[230:231], v[230:231], v[234:235]
	v_pk_add_f32 v[232:233], v[232:233], v[234:235]
	v_rcp_f32_e32 v226, v226
	v_rcp_f32_e32 v227, v227
	v_rcp_f32_e32 v228, v228
	v_rcp_f32_e32 v229, v229
	v_rcp_f32_e32 v230, v230
	v_rcp_f32_e32 v231, v231
	v_rcp_f32_e32 v232, v232
	v_rcp_f32_e32 v233, v233
	v_pk_mul_f32 v[106:107], v[106:107], v[178:179] op_sel_hi:[1,0]
	v_pk_mul_f32 v[108:109], v[108:109], v[178:179] op_sel_hi:[1,0]
	v_pk_mul_f32 v[98:99], v[98:99], v[178:179] op_sel_hi:[1,0]
	v_pk_mul_f32 v[100:101], v[100:101], v[178:179] op_sel_hi:[1,0]
	v_pk_mul_f32 v[106:107], v[106:107], v[226:227]
	v_pk_mul_f32 v[108:109], v[108:109], v[228:229]
	v_pk_mul_f32 v[98:99], v[98:99], v[230:231]
	v_pk_mul_f32 v[100:101], v[100:101], v[232:233]
	v_cvt_pk_bf16_f32 v102, v106, v107
	v_cvt_pk_bf16_f32 v103, v108, v109
	v_cvt_pk_bf16_f32 v104, v98, v99
	v_cvt_pk_bf16_f32 v105, v100, v101
	global_store_dwordx4 v[236:237], v[102:105], off
	v_lshl_add_u64 v[236:237], v[236:237], 0, s[26:27]
	v_pk_mul_f32 v[218:219], v[94:95], v[180:181] op_sel_hi:[1,0]
	v_pk_mul_f32 v[220:221], v[96:97], v[180:181] op_sel_hi:[1,0]
	v_pk_mul_f32 v[222:223], v[86:87], v[180:181] op_sel_hi:[1,0]
	v_pk_mul_f32 v[224:225], v[88:89], v[180:181] op_sel_hi:[1,0]
	v_exp_f32_e32 v218, v218
	v_exp_f32_e32 v219, v219
	v_exp_f32_e32 v220, v220
	v_exp_f32_e32 v221, v221
	v_exp_f32_e32 v222, v222
	v_exp_f32_e32 v223, v223
	v_exp_f32_e32 v224, v224
	v_exp_f32_e32 v225, v225
	v_pk_add_f32 v[218:219], v[218:219], v[234:235]
	v_pk_add_f32 v[220:221], v[220:221], v[234:235]
	v_pk_add_f32 v[222:223], v[222:223], v[234:235]
	v_pk_add_f32 v[224:225], v[224:225], v[234:235]
	v_rcp_f32_e32 v218, v218
	v_rcp_f32_e32 v219, v219
	v_rcp_f32_e32 v220, v220
	v_rcp_f32_e32 v221, v221
	v_rcp_f32_e32 v222, v222
	v_rcp_f32_e32 v223, v223
	v_rcp_f32_e32 v224, v224
	v_rcp_f32_e32 v225, v225
	v_pk_mul_f32 v[90:91], v[90:91], v[182:183] op_sel_hi:[1,0]
	v_pk_mul_f32 v[92:93], v[92:93], v[182:183] op_sel_hi:[1,0]
	v_pk_mul_f32 v[82:83], v[82:83], v[182:183] op_sel_hi:[1,0]
	v_pk_mul_f32 v[84:85], v[84:85], v[182:183] op_sel_hi:[1,0]
	v_pk_mul_f32 v[90:91], v[90:91], v[218:219]
	v_pk_mul_f32 v[92:93], v[92:93], v[220:221]
	v_pk_mul_f32 v[82:83], v[82:83], v[222:223]
	v_pk_mul_f32 v[84:85], v[84:85], v[224:225]
	v_cvt_pk_bf16_f32 v86, v90, v91
	v_cvt_pk_bf16_f32 v87, v92, v93
	v_cvt_pk_bf16_f32 v88, v82, v83
	v_cvt_pk_bf16_f32 v89, v84, v85
	global_store_dwordx4 v[236:237], v[86:89], off
	v_lshl_add_u64 v[236:237], v[236:237], 0, s[26:27]
	v_pk_mul_f32 v[226:227], v[78:79], v[184:185] op_sel_hi:[1,0]
	v_pk_mul_f32 v[228:229], v[80:81], v[184:185] op_sel_hi:[1,0]
	v_pk_mul_f32 v[230:231], v[70:71], v[184:185] op_sel_hi:[1,0]
	v_pk_mul_f32 v[232:233], v[72:73], v[184:185] op_sel_hi:[1,0]
	v_exp_f32_e32 v226, v226
	v_exp_f32_e32 v227, v227
	v_exp_f32_e32 v228, v228
	v_exp_f32_e32 v229, v229
	v_exp_f32_e32 v230, v230
	v_exp_f32_e32 v231, v231
	v_exp_f32_e32 v232, v232
	v_exp_f32_e32 v233, v233
	v_pk_add_f32 v[226:227], v[226:227], v[234:235]
	v_pk_add_f32 v[228:229], v[228:229], v[234:235]
	v_pk_add_f32 v[230:231], v[230:231], v[234:235]
	v_pk_add_f32 v[232:233], v[232:233], v[234:235]
	v_rcp_f32_e32 v226, v226
	v_rcp_f32_e32 v227, v227
	v_rcp_f32_e32 v228, v228
	v_rcp_f32_e32 v229, v229
	v_rcp_f32_e32 v230, v230
	v_rcp_f32_e32 v231, v231
	v_rcp_f32_e32 v232, v232
	v_rcp_f32_e32 v233, v233
	v_pk_mul_f32 v[74:75], v[74:75], v[186:187] op_sel_hi:[1,0]
	v_pk_mul_f32 v[76:77], v[76:77], v[186:187] op_sel_hi:[1,0]
	v_pk_mul_f32 v[66:67], v[66:67], v[186:187] op_sel_hi:[1,0]
	v_pk_mul_f32 v[68:69], v[68:69], v[186:187] op_sel_hi:[1,0]
	v_pk_mul_f32 v[74:75], v[74:75], v[226:227]
	v_pk_mul_f32 v[76:77], v[76:77], v[228:229]
	v_pk_mul_f32 v[66:67], v[66:67], v[230:231]
	v_pk_mul_f32 v[68:69], v[68:69], v[232:233]
	v_cvt_pk_bf16_f32 v70, v74, v75
	v_cvt_pk_bf16_f32 v71, v76, v77
	v_cvt_pk_bf16_f32 v72, v66, v67
	v_cvt_pk_bf16_f32 v73, v68, v69
	global_store_dwordx4 v[236:237], v[70:73], off
	v_lshl_add_u64 v[236:237], v[236:237], 0, s[24:25]
	v_pk_mul_f32 v[218:219], v[62:63], v[188:189] op_sel_hi:[1,0]
	v_pk_mul_f32 v[220:221], v[64:65], v[188:189] op_sel_hi:[1,0]
	v_pk_mul_f32 v[222:223], v[54:55], v[188:189] op_sel_hi:[1,0]
	v_pk_mul_f32 v[224:225], v[56:57], v[188:189] op_sel_hi:[1,0]
	v_exp_f32_e32 v218, v218
	v_exp_f32_e32 v219, v219
	v_exp_f32_e32 v220, v220
	v_exp_f32_e32 v221, v221
	v_exp_f32_e32 v222, v222
	v_exp_f32_e32 v223, v223
	v_exp_f32_e32 v224, v224
	v_exp_f32_e32 v225, v225
	v_pk_add_f32 v[218:219], v[218:219], v[234:235]
	v_pk_add_f32 v[220:221], v[220:221], v[234:235]
	v_pk_add_f32 v[222:223], v[222:223], v[234:235]
; __device__ __forceinline__ unsigned cvt_pk_bf16(float lo, float hi) { f32x2_cv v = {lo, hi}; bf16x2_cv b = __builtin_convertvector(v, bf16x2_cv); return __builtin_bit_cast(unsigned, b); }
; template <class Epi, class Sched, bool ALIGN_EPI = false, bool SP2 = false>
; __device__ __forceinline__ void gemm_phase(PG8_LAS unsigned char* lds, const Gemm g, const Sched& S, const Epi& E) {
;     ...
;         if constexpr (!Epi::AFTER_DRAIN) { E(acc, cur, wr, wc, fr, fq); S.done(cur); }
;         if (!has_next) break;
;     __device__ __forceinline__ void operator()(const f32x4 (&acc)[2][2][4][2], const Unit& u, int wr, int wc, int fr, int fq) const {
;     ...
;             for (int m = 0; m < 4; ++m) {
;                 const int row = row0 + ai * HALF + m * 16; const float rs = row_rstd(rsp, row, fq);
;                 const float nrs = -LOG2E * rs, rs2 = rs * rs;
;                 const f32x4 g0 = acc[ai][0][m][0], g1 = acc[ai][0][m][1], u0 = acc[ai][1][m][0], u1 = acc[ai][1][m][1];
;                 const f32x4 a0 = g0 * nrs, a1 = g1 * nrs;
;                 f32x4 e0, e1;
; #pragma unroll
;                 for (int q = 0; q < 4; ++q) { e0[q] = __builtin_amdgcn_exp2f(a0[q]); e1[q] = __builtin_amdgcn_exp2f(a1[q]); }
;                 const f32x4 d0 = e0 + 1.0f, d1 = e1 + 1.0f;
;                 f32x4 r0, r1;
; #pragma unroll
;                 for (int q = 0; q < 4; ++q) { r0[q] = __builtin_amdgcn_rcpf(d0[q]); r1[q] = __builtin_amdgcn_rcpf(d1[q]); }
;                 const f32x4 o0 = ((g0 * u0) * rs2) * r0, o1 = ((g1 * u1) * rs2) * r1;
;                 u32x4 w; w.x = cvt_pk_bf16(o0[0], o0[1]); w.y = cvt_pk_bf16(o0[2], o0[3]); w.z = cvt_pk_bf16(o1[0], o1[1]); w.w = cvt_pk_bf16(o1[2], o1[3]);
;                 *(u32x4*)(O + (size_t)row * ldc + col0) = w;
	v_pk_add_f32 v[224:225], v[224:225], v[234:235]
	v_rcp_f32_e32 v218, v218
	v_rcp_f32_e32 v219, v219
	v_rcp_f32_e32 v220, v220
	v_rcp_f32_e32 v221, v221
	v_rcp_f32_e32 v222, v222
	v_rcp_f32_e32 v223, v223
	v_rcp_f32_e32 v224, v224
	v_rcp_f32_e32 v225, v225
	v_pk_mul_f32 v[58:59], v[58:59], v[190:191] op_sel_hi:[1,0]
	v_pk_mul_f32 v[60:61], v[60:61], v[190:191] op_sel_hi:[1,0]
	v_pk_mul_f32 v[50:51], v[50:51], v[190:191] op_sel_hi:[1,0]
	v_pk_mul_f32 v[52:53], v[52:53], v[190:191] op_sel_hi:[1,0]
	v_pk_mul_f32 v[58:59], v[58:59], v[218:219]
	v_pk_mul_f32 v[60:61], v[60:61], v[220:221]
	v_pk_mul_f32 v[50:51], v[50:51], v[222:223]
	v_pk_mul_f32 v[52:53], v[52:53], v[224:225]
	v_cvt_pk_bf16_f32 v54, v58, v59
	v_cvt_pk_bf16_f32 v55, v60, v61
	v_cvt_pk_bf16_f32 v56, v50, v51
	v_cvt_pk_bf16_f32 v57, v52, v53
	global_store_dwordx4 v[236:237], v[54:57], off
	v_lshl_add_u64 v[236:237], v[236:237], 0, s[26:27]
	v_pk_mul_f32 v[226:227], v[46:47], v[192:193] op_sel_hi:[1,0]
	v_pk_mul_f32 v[228:229], v[48:49], v[192:193] op_sel_hi:[1,0]
	v_pk_mul_f32 v[230:231], v[38:39], v[192:193] op_sel_hi:[1,0]
	v_pk_mul_f32 v[232:233], v[40:41], v[192:193] op_sel_hi:[1,0]
	v_exp_f32_e32 v226, v226
	v_exp_f32_e32 v227, v227
	v_exp_f32_e32 v228, v228
	v_exp_f32_e32 v229, v229
	v_exp_f32_e32 v230, v230
	v_exp_f32_e32 v231, v231
	v_exp_f32_e32 v232, v232
	v_exp_f32_e32 v233, v233
	v_pk_add_f32 v[226:227], v[226:227], v[234:235]
	v_pk_add_f32 v[228:229], v[228:229], v[234:235]
	v_pk_add_f32 v[230:231], v[230:231], v[234:235]
	v_pk_add_f32 v[232:233], v[232:233], v[234:235]
	v_rcp_f32_e32 v226, v226
	v_rcp_f32_e32 v227, v227
	v_rcp_f32_e32 v228, v228
	v_rcp_f32_e32 v229, v229
	v_rcp_f32_e32 v230, v230
	v_rcp_f32_e32 v231, v231
	v_rcp_f32_e32 v232, v232
	v_rcp_f32_e32 v233, v233
	v_pk_mul_f32 v[42:43], v[42:43], v[194:195] op_sel_hi:[1,0]
	v_pk_mul_f32 v[44:45], v[44:45], v[194:195] op_sel_hi:[1,0]
	v_pk_mul_f32 v[34:35], v[34:35], v[194:195] op_sel_hi:[1,0]
	v_pk_mul_f32 v[36:37], v[36:37], v[194:195] op_sel_hi:[1,0]
	v_pk_mul_f32 v[42:43], v[42:43], v[226:227]
	v_pk_mul_f32 v[44:45], v[44:45], v[228:229]
	v_pk_mul_f32 v[34:35], v[34:35], v[230:231]
	v_pk_mul_f32 v[36:37], v[36:37], v[232:233]
	v_cvt_pk_bf16_f32 v38, v42, v43
	v_cvt_pk_bf16_f32 v39, v44, v45
	v_cvt_pk_bf16_f32 v40, v34, v35
	v_cvt_pk_bf16_f32 v41, v36, v37
	global_store_dwordx4 v[236:237], v[38:41], off
	v_lshl_add_u64 v[236:237], v[236:237], 0, s[26:27]
	v_pk_mul_f32 v[218:219], v[30:31], v[196:197] op_sel_hi:[1,0]
	v_pk_mul_f32 v[220:221], v[32:33], v[196:197] op_sel_hi:[1,0]
	v_pk_mul_f32 v[222:223], v[22:23], v[196:197] op_sel_hi:[1,0]
	v_pk_mul_f32 v[224:225], v[24:25], v[196:197] op_sel_hi:[1,0]
	v_exp_f32_e32 v218, v218
	v_exp_f32_e32 v219, v219
	v_exp_f32_e32 v220, v220
	v_exp_f32_e32 v221, v221
	v_exp_f32_e32 v222, v222
	v_exp_f32_e32 v223, v223
	v_exp_f32_e32 v224, v224
	v_exp_f32_e32 v225, v225
	v_pk_add_f32 v[218:219], v[218:219], v[234:235]
	v_pk_add_f32 v[220:221], v[220:221], v[234:235]
	v_pk_add_f32 v[222:223], v[222:223], v[234:235]
	v_pk_add_f32 v[224:225], v[224:225], v[234:235]
	v_rcp_f32_e32 v218, v218
	v_rcp_f32_e32 v219, v219
	v_rcp_f32_e32 v220, v220
	v_rcp_f32_e32 v221, v221
	v_rcp_f32_e32 v222, v222
	v_rcp_f32_e32 v223, v223
	v_rcp_f32_e32 v224, v224
	v_rcp_f32_e32 v225, v225
	v_pk_mul_f32 v[26:27], v[26:27], v[198:199] op_sel_hi:[1,0]
	v_pk_mul_f32 v[28:29], v[28:29], v[198:199] op_sel_hi:[1,0]
	v_pk_mul_f32 v[18:19], v[18:19], v[198:199] op_sel_hi:[1,0]
	v_pk_mul_f32 v[20:21], v[20:21], v[198:199] op_sel_hi:[1,0]
	v_pk_mul_f32 v[26:27], v[26:27], v[218:219]
	v_pk_mul_f32 v[28:29], v[28:29], v[220:221]
	v_pk_mul_f32 v[18:19], v[18:19], v[222:223]
	v_pk_mul_f32 v[20:21], v[20:21], v[224:225]
	v_cvt_pk_bf16_f32 v22, v26, v27
	v_cvt_pk_bf16_f32 v23, v28, v29
	v_cvt_pk_bf16_f32 v24, v18, v19
	v_cvt_pk_bf16_f32 v25, v20, v21
	global_store_dwordx4 v[236:237], v[22:25], off
	v_lshl_add_u64 v[236:237], v[236:237], 0, s[26:27]
	v_pk_mul_f32 v[226:227], v[14:15], v[214:215] op_sel_hi:[1,0]
	v_pk_mul_f32 v[228:229], v[16:17], v[214:215] op_sel_hi:[1,0]
	v_pk_mul_f32 v[230:231], v[6:7], v[214:215] op_sel_hi:[1,0]
	v_pk_mul_f32 v[232:233], v[8:9], v[214:215] op_sel_hi:[1,0]
	v_exp_f32_e32 v226, v226
	v_exp_f32_e32 v227, v227
	v_exp_f32_e32 v228, v228
	v_exp_f32_e32 v229, v229
	v_exp_f32_e32 v230, v230
	v_exp_f32_e32 v231, v231
	v_exp_f32_e32 v232, v232
	v_exp_f32_e32 v233, v233
	v_pk_add_f32 v[226:227], v[226:227], v[234:235]
	v_pk_add_f32 v[228:229], v[228:229], v[234:235]
	v_pk_add_f32 v[230:231], v[230:231], v[234:235]
	v_pk_add_f32 v[232:233], v[232:233], v[234:235]
	v_rcp_f32_e32 v226, v226
	v_rcp_f32_e32 v227, v227
	v_rcp_f32_e32 v228, v228
	v_rcp_f32_e32 v229, v229
	v_rcp_f32_e32 v230, v230
	v_rcp_f32_e32 v231, v231
	v_rcp_f32_e32 v232, v232
	v_rcp_f32_e32 v233, v233
	v_pk_mul_f32 v[10:11], v[10:11], v[216:217] op_sel_hi:[1,0]
	v_pk_mul_f32 v[12:13], v[12:13], v[216:217] op_sel_hi:[1,0]
	v_pk_mul_f32 v[2:3], v[2:3], v[216:217] op_sel_hi:[1,0]
	v_pk_mul_f32 v[4:5], v[4:5], v[216:217] op_sel_hi:[1,0]
	v_pk_mul_f32 v[10:11], v[10:11], v[226:227]
	v_pk_mul_f32 v[12:13], v[12:13], v[228:229]
	v_pk_mul_f32 v[2:3], v[2:3], v[230:231]
	v_pk_mul_f32 v[4:5], v[4:5], v[232:233]
	v_cvt_pk_bf16_f32 v6, v10, v11
	v_cvt_pk_bf16_f32 v7, v12, v13
	v_cvt_pk_bf16_f32 v8, v2, v3
	v_cvt_pk_bf16_f32 v9, v4, v5
	global_store_dwordx4 v[236:237], v[6:9], off
	s_mov_b64 s[22:23], -1
	s_andn2_b64 vcc, exec, s[4:5]
	s_cbranch_vccnz .LBB0_489
	s_andn2_b64 vcc, exec, s[8:9]
	s_cbranch_vccnz .LBB0_488
	s_barrier
	s_branch .LBB0_488
